# MoE1 epilogue silu via v_rcp_f32 instead of the IEEE division expansion; expert lookup vectorised (one 32-lane compare + popcount)
# speedup vs baseline: 1.0144x; 1.0080x over previous
.LBB0_1723:
	v_mbcnt_lo_u32_b32 v2, -1, 0
	v_mbcnt_hi_u32_b32 v2, -1, v2
	v_lshlrev_b32_e32 v2, 2, v2
	v_add_u32_e32 v2, 0x22000, v2
	ds_read_b32 v3, v2
	s_mov_b32 s20, 0x78
	s_mov_b32 s21, 0x22074
	s_mov_b32 s9, 31
	s_mov_b32 s8, 32
	s_mov_b32 s5, 0x22080
	s_waitcnt lgkmcnt(0)
	v_cmp_ge_i32_e32 vcc, s4, v3
	s_and_b32 s20, vcc_lo, -2
	s_bcnt1_i32_b32 s20, s20
	v_mov_b32_e32 v2, s20
	s_mov_b32 s20, 0x78
.LBB0_1725:
	v_lshlrev_b32_e32 v0, 2, v2
	v_add_u32_e32 v0, 0, v0
	v_add_u32_e32 v0, 0x22000, v0
	ds_read2_b32 v[4:5], v0 offset1:40
	ds_read_b32 v1, v0 offset:320
	v_mov_b32_e32 v3, 0
	s_waitcnt lgkmcnt(1)
	v_readfirstlane_b32 s5, v5
	s_abs_i32 s8, s5
	v_cvt_f32_u32_e32 v5, s8
	v_readfirstlane_b32 s9, v4
	s_sub_i32 s21, 0, s8
	s_sub_i32 s9, s4, s9
	v_rcp_iflag_f32_e32 v5, v5
	s_abs_i32 s20, s9
	s_xor_b32 s4, s9, s5
	s_ashr_i32 s4, s4, 31
	v_mul_f32_e32 v4, 0x4f7ffffe, v5
	v_cvt_u32_f32_e32 v4, v4
	s_nop 0
	v_readfirstlane_b32 s22, v4
	s_mul_i32 s21, s21, s22
	s_mul_hi_u32 s21, s22, s21
	s_add_i32 s22, s22, s21
	s_mul_hi_u32 s21, s20, s22
	s_mul_i32 s22, s21, s8
	s_sub_i32 s20, s20, s22
	s_add_i32 s23, s21, 1
	s_sub_i32 s22, s20, s8
	s_cmp_ge_u32 s20, s8
	s_cselect_b32 s21, s23, s21
	s_cselect_b32 s20, s22, s20
	s_add_i32 s22, s21, 1
	s_cmp_ge_u32 s20, s8
	s_cselect_b32 s8, s22, s21
	s_xor_b32 s8, s8, s4
	s_sub_i32 s4, s8, s4
	s_mul_i32 s5, s4, s5
	s_sub_i32 s5, s9, s5
	s_lshl_b32 s22, s5, 8
	s_cmp_lg_u64 s[16:17], 0
	s_cselect_b64 s[20:21], -1, 0
	s_mov_b64 s[8:9], 0
	s_and_b64 vcc, exec, s[20:21]
	s_cbranch_vccz .LBB0_1767
	ds_read_b32 v0, v0 offset:480
	v_lshlrev_b64 v[4:5], 17, v[2:3]
	s_ashr_i32 s23, s22, 31
	v_lshl_add_u64 v[4:5], s[16:17], 0, v[4:5]
	s_lshl_b64 s[24:25], s[22:23], 2
	s_not_b32 s5, s22
	v_lshl_add_u64 v[4:5], v[4:5], 0, s[24:25]
	s_waitcnt lgkmcnt(0)
	v_add_u32_e32 v6, s5, v0
	v_add_u32_e32 v198, s22, v1
	s_andn2_b64 vcc, exec, s[8:9]
	v_mov_b64_e32 v[0:1], s[12:13]
	s_cbranch_vccnz .LBB0_1729

.LBB0_1732:
	v_mul_f32_e32 v129, 0xbfb8aa3b, v124
	v_exp_f32_e32 v132, v129
	s_ashr_i32 s6, s82, 1
	v_add_u32_e32 v130, s6, v212
	v_add_u32_e32 v128, v198, v210
	v_add_f32_e32 v132, 1.0, v132
	v_rcp_f32_e32 v134, v132
	v_ashrrev_i32_e32 v129, 31, v128
	v_lshlrev_b64 v[128:129], 11, v[128:129]
	v_ashrrev_i32_e32 v131, 31, v130
	v_lshl_add_u64 v[128:129], s[14:15], 0, v[128:129]
	v_lshl_add_u64 v[128:129], v[130:131], 1, v[128:129]
	v_mul_f32_e32 v135, 0xbfb8aa3b, v125
	v_exp_f32_e32 v135, v135
	s_nop 0
	v_add_f32_e32 v133, 1.0, v135
	v_rcp_f32_e32 v136, v133
	v_mul_f32_e32 v130, v124, v134
	v_mov_b32_e32 v124, v130
	v_mul_f32_e32 v120, v124, v120
	v_mul_f32_e32 v131, 0xbfb8aa3b, v126
	v_exp_f32_e32 v131, v131
	v_mul_f32_e32 v124, v125, v136
	v_add_f32_e32 v130, 1.0, v131
	v_rcp_f32_e32 v132, v130
	v_mul_f32_e32 v121, v124, v121
	v_mul_f32_e32 v125, 0xbfb8aa3b, v127
	v_cvt_pk_bf16_f32 v120, v120, v121
	v_exp_f32_e32 v125, v125
	s_nop 0
	v_add_f32_e32 v125, 1.0, v125
	v_rcp_f32_e32 v133, v125
	v_mul_f32_e32 v121, v126, v132
	v_mul_f32_e32 v121, v121, v122
	v_mul_f32_e32 v126, 0xbfb8aa3b, v116
	v_exp_f32_e32 v126, v126
	v_mul_f32_e32 v122, v127, v133
	v_add_f32_e32 v124, 1.0, v126
	v_rcp_f32_e32 v126, v124
	v_mul_f32_e32 v122, v122, v123
	v_cvt_pk_bf16_f32 v121, v121, v122
	v_mul_f32_e32 v122, 0xbfb8aa3b, v117
	v_exp_f32_e32 v122, v122
	global_store_dwordx2 v[128:129], v[120:121], off
	v_add_f32_e32 v122, 1.0, v122
	v_rcp_f32_e32 v125, v122
	v_mul_f32_e32 v120, v116, v126
	v_mov_b32_e32 v116, v120
	v_mul_f32_e32 v112, v116, v112
	v_mul_f32_e32 v121, 0xbfb8aa3b, v118
	v_exp_f32_e32 v121, v121
	v_mul_f32_e32 v116, v117, v125
	v_add_f32_e32 v120, 1.0, v121
	v_rcp_f32_e32 v123, v120
	v_mul_f32_e32 v113, v116, v113
	v_mul_f32_e32 v117, 0xbfb8aa3b, v119
	v_cvt_pk_bf16_f32 v112, v112, v113
	v_exp_f32_e32 v117, v117
	s_nop 0
	v_add_f32_e32 v117, 1.0, v117
	v_rcp_f32_e32 v122, v117
	v_mul_f32_e32 v113, v118, v123
	v_mul_f32_e32 v113, v113, v114
	v_mul_f32_e32 v118, 0xbfb8aa3b, v108
	v_exp_f32_e32 v118, v118
	v_mul_f32_e32 v114, v119, v122
	v_mul_f32_e32 v114, v114, v115
	v_add_f32_e32 v115, 1.0, v118
	v_rcp_f32_e32 v117, v115
	v_cvt_pk_bf16_f32 v113, v113, v114
	v_mul_f32_e32 v119, 0xbfb8aa3b, v109
	v_exp_f32_e32 v119, v119
	s_nop 0
	v_add_f32_e32 v116, 1.0, v119
	v_rcp_f32_e32 v120, v116
	v_mul_f32_e32 v114, v108, v117
	v_mov_b32_e32 v108, v114
	v_mul_f32_e32 v104, v108, v104
	v_mul_f32_e32 v115, 0xbfb8aa3b, v110
	v_exp_f32_e32 v115, v115
	v_mul_f32_e32 v108, v109, v120
	v_add_f32_e32 v114, 1.0, v115
	v_rcp_f32_e32 v117, v114
	v_mul_f32_e32 v105, v108, v105
	v_mul_f32_e32 v109, 0xbfb8aa3b, v111
	global_store_dwordx2 v[128:129], v[112:113], off offset:32
	v_cvt_pk_bf16_f32 v104, v104, v105
	v_exp_f32_e32 v109, v109
	s_nop 0
	v_add_f32_e32 v109, 1.0, v109
	v_rcp_f32_e32 v116, v109
	v_mul_f32_e32 v105, v110, v117
	v_mul_f32_e32 v105, v105, v106
	v_mul_f32_e32 v106, v111, v116
	v_mul_f32_e32 v108, 0xbfb8aa3b, v100
	v_exp_f32_e32 v108, v108
	v_mul_f32_e32 v106, v106, v107
	v_cvt_pk_bf16_f32 v105, v105, v106
	v_add_f32_e32 v108, 1.0, v108
	v_rcp_f32_e32 v110, v108
	v_add_co_u32_e32 v106, vcc, s73, v128
	v_lshl_add_u64 v[112:113], v[128:129], 0, s[30:31]
	s_nop 0
	v_addc_co_u32_e32 v107, vcc, 0, v129, vcc
	global_store_dwordx2 v[106:107], v[104:105], off
	v_mul_f32_e32 v106, 0xbfb8aa3b, v101
	v_exp_f32_e32 v106, v106
	s_nop 0
	v_add_f32_e32 v106, 1.0, v106
	v_rcp_f32_e32 v109, v106
	v_mul_f32_e32 v104, v100, v110
	v_mov_b32_e32 v100, v104
	v_mul_f32_e32 v96, v100, v96
	v_mul_f32_e32 v105, 0xbfb8aa3b, v102
	v_exp_f32_e32 v105, v105
	v_mul_f32_e32 v100, v101, v109
	v_add_f32_e32 v104, 1.0, v105
	v_rcp_f32_e32 v107, v104
	v_mul_f32_e32 v97, v100, v97
	v_mul_f32_e32 v101, 0xbfb8aa3b, v103
	v_cvt_pk_bf16_f32 v96, v96, v97
	v_exp_f32_e32 v101, v101
	s_nop 0
	v_add_f32_e32 v101, 1.0, v101
	v_rcp_f32_e32 v106, v101
	v_mul_f32_e32 v97, v102, v107
	v_mul_f32_e32 v97, v97, v98
	v_mul_f32_e32 v102, 0xbfb8aa3b, v92
	v_exp_f32_e32 v102, v102
	v_mul_f32_e32 v98, v103, v106
	v_mul_f32_e32 v98, v98, v99
	v_add_f32_e32 v99, 1.0, v102
	v_rcp_f32_e32 v101, v99
	v_cvt_pk_bf16_f32 v97, v97, v98
	v_mul_f32_e32 v103, 0xbfb8aa3b, v93
	v_exp_f32_e32 v103, v103
	s_nop 0
	v_add_f32_e32 v100, 1.0, v103
	v_rcp_f32_e32 v104, v100
	v_mul_f32_e32 v98, v92, v101
	v_mov_b32_e32 v92, v98
	v_mul_f32_e32 v88, v92, v88
	v_mul_f32_e32 v99, 0xbfb8aa3b, v94
	v_exp_f32_e32 v99, v99
	v_mul_f32_e32 v92, v93, v104
	v_add_f32_e32 v98, 1.0, v99
	v_rcp_f32_e32 v101, v98
	v_mul_f32_e32 v89, v92, v89
	v_mul_f32_e32 v93, 0xbfb8aa3b, v95
	global_store_dwordx2 v[112:113], v[96:97], off offset:32
	v_cvt_pk_bf16_f32 v88, v88, v89
	v_exp_f32_e32 v93, v93
	s_nop 0
	v_add_f32_e32 v93, 1.0, v93
	v_rcp_f32_e32 v100, v93
	v_mul_f32_e32 v89, v94, v101
	v_mul_f32_e32 v89, v89, v90
	v_mul_f32_e32 v90, v95, v100
	v_mul_f32_e32 v92, 0xbfb8aa3b, v84
	v_exp_f32_e32 v92, v92
	v_mul_f32_e32 v90, v90, v91
	v_cvt_pk_bf16_f32 v89, v89, v90
	v_add_f32_e32 v92, 1.0, v92
	v_rcp_f32_e32 v94, v92
	v_add_co_u32_e32 v90, vcc, s69, v128
	v_lshl_add_u64 v[96:97], v[128:129], 0, s[34:35]
	s_nop 0
	v_addc_co_u32_e32 v91, vcc, 0, v129, vcc
	global_store_dwordx2 v[90:91], v[88:89], off
	v_mul_f32_e32 v90, 0xbfb8aa3b, v85
	v_exp_f32_e32 v90, v90
	s_nop 0
	v_add_f32_e32 v90, 1.0, v90
	v_rcp_f32_e32 v93, v90
	v_mul_f32_e32 v88, v84, v94
	v_mov_b32_e32 v84, v88
	v_mul_f32_e32 v80, v84, v80
	v_mul_f32_e32 v89, 0xbfb8aa3b, v86
	v_exp_f32_e32 v89, v89
	v_mul_f32_e32 v84, v85, v93
	v_add_f32_e32 v88, 1.0, v89
	v_rcp_f32_e32 v91, v88
	v_mul_f32_e32 v81, v84, v81
	v_mul_f32_e32 v85, 0xbfb8aa3b, v87
	v_cvt_pk_bf16_f32 v80, v80, v81
	v_exp_f32_e32 v85, v85
	s_nop 0
	v_add_f32_e32 v85, 1.0, v85
	v_rcp_f32_e32 v90, v85
	v_mul_f32_e32 v81, v86, v91
	v_mul_f32_e32 v81, v81, v82
	v_mul_f32_e32 v86, 0xbfb8aa3b, v76
	v_exp_f32_e32 v86, v86
	v_mul_f32_e32 v82, v87, v90
	v_mul_f32_e32 v82, v82, v83
	v_add_f32_e32 v83, 1.0, v86
	v_rcp_f32_e32 v85, v83
	v_cvt_pk_bf16_f32 v81, v81, v82
	v_mul_f32_e32 v87, 0xbfb8aa3b, v77
	v_exp_f32_e32 v87, v87
	s_nop 0
	v_add_f32_e32 v84, 1.0, v87
	v_rcp_f32_e32 v88, v84
	v_mul_f32_e32 v82, v76, v85
	v_mov_b32_e32 v76, v82
	v_mul_f32_e32 v72, v76, v72
	v_mul_f32_e32 v83, 0xbfb8aa3b, v78
	v_exp_f32_e32 v83, v83
	v_mul_f32_e32 v76, v77, v88
	v_add_f32_e32 v82, 1.0, v83
	v_rcp_f32_e32 v85, v82
	v_mul_f32_e32 v73, v76, v73
	v_mul_f32_e32 v77, 0xbfb8aa3b, v79
	global_store_dwordx2 v[96:97], v[80:81], off offset:32
	v_cvt_pk_bf16_f32 v72, v72, v73
	v_exp_f32_e32 v77, v77
	s_nop 0
	v_add_f32_e32 v77, 1.0, v77
	v_rcp_f32_e32 v84, v77
	v_mul_f32_e32 v73, v78, v85
	v_mul_f32_e32 v73, v73, v74
	v_mul_f32_e32 v74, v79, v84
	v_mul_f32_e32 v76, 0xbfb8aa3b, v68
	v_exp_f32_e32 v76, v76
	v_mul_f32_e32 v74, v74, v75
	v_cvt_pk_bf16_f32 v73, v73, v74
	v_add_f32_e32 v76, 1.0, v76
	v_rcp_f32_e32 v78, v76
	v_add_co_u32_e32 v74, vcc, s72, v128
	v_lshl_add_u64 v[80:81], v[128:129], 0, s[36:37]
	s_nop 0
	v_addc_co_u32_e32 v75, vcc, 0, v129, vcc
	global_store_dwordx2 v[74:75], v[72:73], off
	v_mul_f32_e32 v74, 0xbfb8aa3b, v69
	v_exp_f32_e32 v74, v74
	s_nop 0
	v_add_f32_e32 v74, 1.0, v74
	v_rcp_f32_e32 v77, v74
	v_mul_f32_e32 v72, v68, v78
	v_mov_b32_e32 v68, v72
	v_mul_f32_e32 v64, v68, v64
	v_mul_f32_e32 v73, 0xbfb8aa3b, v70
	v_exp_f32_e32 v73, v73
	v_mul_f32_e32 v68, v69, v77
	v_add_f32_e32 v72, 1.0, v73
	v_rcp_f32_e32 v75, v72
	v_mul_f32_e32 v65, v68, v65
	v_mul_f32_e32 v69, 0xbfb8aa3b, v71
	v_cvt_pk_bf16_f32 v64, v64, v65
	v_exp_f32_e32 v69, v69
	s_nop 0
	v_add_f32_e32 v69, 1.0, v69
	v_rcp_f32_e32 v74, v69
	v_mul_f32_e32 v65, v70, v75
	v_mul_f32_e32 v65, v65, v66
	v_mul_f32_e32 v70, 0xbfb8aa3b, v60
	v_exp_f32_e32 v70, v70
	v_mul_f32_e32 v66, v71, v74
	v_mul_f32_e32 v66, v66, v67
	v_add_f32_e32 v67, 1.0, v70
	v_rcp_f32_e32 v69, v67
	v_cvt_pk_bf16_f32 v65, v65, v66
	v_mul_f32_e32 v71, 0xbfb8aa3b, v61
	v_exp_f32_e32 v71, v71
	s_nop 0
	v_add_f32_e32 v68, 1.0, v71
	v_rcp_f32_e32 v72, v68
	v_mul_f32_e32 v66, v60, v69
	v_mov_b32_e32 v60, v66
	v_mul_f32_e32 v56, v60, v56
	v_mul_f32_e32 v67, 0xbfb8aa3b, v62
	v_exp_f32_e32 v67, v67
	v_mul_f32_e32 v60, v61, v72
	v_add_f32_e32 v66, 1.0, v67
	v_rcp_f32_e32 v69, v66
	v_mul_f32_e32 v57, v60, v57
	v_mul_f32_e32 v61, 0xbfb8aa3b, v63
	global_store_dwordx2 v[80:81], v[64:65], off offset:32
	v_cvt_pk_bf16_f32 v56, v56, v57
	v_exp_f32_e32 v61, v61
	s_nop 0
	v_add_f32_e32 v61, 1.0, v61
	v_rcp_f32_e32 v68, v61
	v_mul_f32_e32 v57, v62, v69
	v_mul_f32_e32 v57, v57, v58
	v_mul_f32_e32 v58, v63, v68
	v_mul_f32_e32 v60, 0xbfb8aa3b, v52
	v_exp_f32_e32 v60, v60
	v_mul_f32_e32 v58, v58, v59
	v_cvt_pk_bf16_f32 v57, v57, v58
	v_add_f32_e32 v60, 1.0, v60
	v_rcp_f32_e32 v62, v60
	v_add_co_u32_e32 v58, vcc, s78, v128
	v_lshl_add_u64 v[64:65], v[128:129], 0, s[42:43]
	s_nop 0
	v_addc_co_u32_e32 v59, vcc, 0, v129, vcc
	global_store_dwordx2 v[58:59], v[56:57], off
	v_mul_f32_e32 v58, 0xbfb8aa3b, v53
	v_exp_f32_e32 v58, v58
	s_nop 0
	v_add_f32_e32 v58, 1.0, v58
	v_rcp_f32_e32 v61, v58
	v_mul_f32_e32 v56, v52, v62
	v_mov_b32_e32 v52, v56
	v_mul_f32_e32 v48, v52, v48
	v_mul_f32_e32 v57, 0xbfb8aa3b, v54
	v_exp_f32_e32 v57, v57
	v_mul_f32_e32 v52, v53, v61
	v_add_f32_e32 v56, 1.0, v57
	v_rcp_f32_e32 v59, v56
	v_mul_f32_e32 v49, v52, v49
	v_mul_f32_e32 v53, 0xbfb8aa3b, v55
	v_cvt_pk_bf16_f32 v48, v48, v49
	v_exp_f32_e32 v53, v53
	s_nop 0
	v_add_f32_e32 v53, 1.0, v53
	v_rcp_f32_e32 v58, v53
	v_mul_f32_e32 v49, v54, v59
	v_mul_f32_e32 v49, v49, v50
	v_mul_f32_e32 v54, 0xbfb8aa3b, v44
	v_exp_f32_e32 v54, v54
	v_mul_f32_e32 v50, v55, v58
	v_mul_f32_e32 v50, v50, v51
	v_add_f32_e32 v51, 1.0, v54
	v_rcp_f32_e32 v53, v51
	v_cvt_pk_bf16_f32 v49, v49, v50
	v_mul_f32_e32 v55, 0xbfb8aa3b, v45
	v_exp_f32_e32 v55, v55
	s_nop 0
	v_add_f32_e32 v52, 1.0, v55
	v_rcp_f32_e32 v56, v52
	v_mul_f32_e32 v50, v44, v53
	v_mov_b32_e32 v44, v50
	v_mul_f32_e32 v40, v44, v40
	v_mul_f32_e32 v51, 0xbfb8aa3b, v46
	v_exp_f32_e32 v51, v51
	v_mul_f32_e32 v44, v45, v56
	v_add_f32_e32 v50, 1.0, v51
	v_rcp_f32_e32 v53, v50
	v_mul_f32_e32 v41, v44, v41
	v_mul_f32_e32 v45, 0xbfb8aa3b, v47
	global_store_dwordx2 v[64:65], v[48:49], off offset:32
	v_cvt_pk_bf16_f32 v40, v40, v41
	v_exp_f32_e32 v45, v45
	s_nop 0
	v_add_f32_e32 v45, 1.0, v45
	v_rcp_f32_e32 v52, v45
	v_mul_f32_e32 v41, v46, v53
	v_mul_f32_e32 v41, v41, v42
	v_mul_f32_e32 v42, v47, v52
	v_mul_f32_e32 v44, 0xbfb8aa3b, v36
	v_exp_f32_e32 v44, v44
	v_mul_f32_e32 v42, v42, v43
	v_cvt_pk_bf16_f32 v41, v41, v42
	v_add_f32_e32 v44, 1.0, v44
	v_rcp_f32_e32 v46, v44
	v_add_co_u32_e32 v42, vcc, s79, v128
	v_lshl_add_u64 v[48:49], v[128:129], 0, s[44:45]
	s_nop 0
	v_addc_co_u32_e32 v43, vcc, 0, v129, vcc
	global_store_dwordx2 v[42:43], v[40:41], off
	v_mul_f32_e32 v42, 0xbfb8aa3b, v37
	v_exp_f32_e32 v42, v42
	s_nop 0
	v_add_f32_e32 v42, 1.0, v42
	v_rcp_f32_e32 v45, v42
	v_mul_f32_e32 v40, v36, v46
	v_mov_b32_e32 v36, v40
	v_mul_f32_e32 v32, v36, v32
	v_mul_f32_e32 v41, 0xbfb8aa3b, v38
	v_exp_f32_e32 v41, v41
	v_mul_f32_e32 v36, v37, v45
	v_add_f32_e32 v40, 1.0, v41
	v_rcp_f32_e32 v43, v40
	v_mul_f32_e32 v33, v36, v33
	v_mul_f32_e32 v37, 0xbfb8aa3b, v39
	v_cvt_pk_bf16_f32 v32, v32, v33
	v_exp_f32_e32 v37, v37
	s_nop 0
	v_add_f32_e32 v37, 1.0, v37
	v_rcp_f32_e32 v42, v37
	v_mul_f32_e32 v33, v38, v43
	v_mul_f32_e32 v33, v33, v34
	v_mul_f32_e32 v38, 0xbfb8aa3b, v28
	v_exp_f32_e32 v38, v38
	v_mul_f32_e32 v34, v39, v42
	v_mul_f32_e32 v34, v34, v35
	v_add_f32_e32 v35, 1.0, v38
	v_rcp_f32_e32 v37, v35
	v_cvt_pk_bf16_f32 v33, v33, v34
	v_mul_f32_e32 v39, 0xbfb8aa3b, v29
	v_exp_f32_e32 v39, v39
	s_nop 0
	v_add_f32_e32 v36, 1.0, v39
	v_rcp_f32_e32 v40, v36
	v_mul_f32_e32 v34, v28, v37
	v_mov_b32_e32 v28, v34
	v_mul_f32_e32 v24, v28, v24
	v_mul_f32_e32 v35, 0xbfb8aa3b, v30
	v_exp_f32_e32 v35, v35
	v_mul_f32_e32 v28, v29, v40
	v_add_f32_e32 v34, 1.0, v35
	v_rcp_f32_e32 v37, v34
	v_mul_f32_e32 v25, v28, v25
	v_mul_f32_e32 v29, 0xbfb8aa3b, v31
	global_store_dwordx2 v[48:49], v[32:33], off offset:32
	v_cvt_pk_bf16_f32 v24, v24, v25
	v_exp_f32_e32 v29, v29
	s_nop 0
	v_add_f32_e32 v29, 1.0, v29
	v_rcp_f32_e32 v36, v29
	v_mul_f32_e32 v25, v30, v37
	v_mul_f32_e32 v25, v25, v26
	v_mul_f32_e32 v26, v31, v36
	v_mul_f32_e32 v28, 0xbfb8aa3b, v20
	v_exp_f32_e32 v28, v28
	v_mul_f32_e32 v26, v26, v27
	v_cvt_pk_bf16_f32 v25, v25, v26
	v_add_f32_e32 v28, 1.0, v28
	v_rcp_f32_e32 v30, v28
	v_add_co_u32_e32 v26, vcc, s80, v128
	v_lshl_add_u64 v[32:33], v[128:129], 0, s[46:47]
	s_nop 0
	v_addc_co_u32_e32 v27, vcc, 0, v129, vcc
	global_store_dwordx2 v[26:27], v[24:25], off
	v_mul_f32_e32 v26, 0xbfb8aa3b, v21
	v_exp_f32_e32 v26, v26
	s_nop 0
	v_add_f32_e32 v26, 1.0, v26
	v_rcp_f32_e32 v29, v26
	v_mul_f32_e32 v24, v20, v30
	v_mov_b32_e32 v20, v24
	v_mul_f32_e32 v16, v20, v16
	v_mul_f32_e32 v25, 0xbfb8aa3b, v22
	v_exp_f32_e32 v25, v25
	v_mul_f32_e32 v20, v21, v29
	v_add_f32_e32 v24, 1.0, v25
	v_rcp_f32_e32 v27, v24
	v_mul_f32_e32 v17, v20, v17
	v_mul_f32_e32 v21, 0xbfb8aa3b, v23
	v_cvt_pk_bf16_f32 v16, v16, v17
	v_exp_f32_e32 v21, v21
	s_nop 0
	v_add_f32_e32 v21, 1.0, v21
	v_rcp_f32_e32 v26, v21
	v_mul_f32_e32 v17, v22, v27
	v_mul_f32_e32 v17, v17, v18
	v_mul_f32_e32 v22, 0xbfb8aa3b, v12
	v_exp_f32_e32 v22, v22
	v_mul_f32_e32 v18, v23, v26
	v_mul_f32_e32 v18, v18, v19
	v_add_f32_e32 v19, 1.0, v22
	v_rcp_f32_e32 v21, v19
	v_cvt_pk_bf16_f32 v17, v17, v18
	v_mul_f32_e32 v23, 0xbfb8aa3b, v13
	v_exp_f32_e32 v23, v23
	s_nop 0
	v_add_f32_e32 v20, 1.0, v23
	v_rcp_f32_e32 v24, v20
	v_mul_f32_e32 v18, v12, v21
	v_mov_b32_e32 v12, v18
	v_mul_f32_e32 v8, v12, v8
	v_mul_f32_e32 v19, 0xbfb8aa3b, v14
	v_exp_f32_e32 v19, v19
	v_mul_f32_e32 v12, v13, v24
	v_add_f32_e32 v18, 1.0, v19
	v_rcp_f32_e32 v21, v18
	v_mul_f32_e32 v9, v12, v9
	v_mul_f32_e32 v13, 0xbfb8aa3b, v15
	global_store_dwordx2 v[32:33], v[16:17], off offset:32
	v_cvt_pk_bf16_f32 v8, v8, v9
	v_exp_f32_e32 v13, v13
	s_nop 0
	v_add_f32_e32 v13, 1.0, v13
	v_rcp_f32_e32 v20, v13
	v_mul_f32_e32 v9, v14, v21
	v_mul_f32_e32 v9, v9, v10
	v_mul_f32_e32 v10, v15, v20
	v_mul_f32_e32 v12, 0xbfb8aa3b, v4
	v_exp_f32_e32 v12, v12
	v_mul_f32_e32 v10, v10, v11
	v_cvt_pk_bf16_f32 v9, v9, v10
	v_add_f32_e32 v12, 1.0, v12
	v_rcp_f32_e32 v14, v12
	v_add_co_u32_e32 v10, vcc, s81, v128
	v_lshl_add_u64 v[16:17], v[128:129], 0, s[48:49]
	s_nop 0
	v_addc_co_u32_e32 v11, vcc, 0, v129, vcc
	global_store_dwordx2 v[10:11], v[8:9], off
	v_mul_f32_e32 v10, 0xbfb8aa3b, v5
	v_exp_f32_e32 v10, v10
	s_nop 0
	v_add_f32_e32 v10, 1.0, v10
	v_rcp_f32_e32 v13, v10
	v_mul_f32_e32 v8, v4, v14
	v_mov_b32_e32 v4, v8
	v_mul_f32_e32 v0, v4, v0
	v_mul_f32_e32 v9, 0xbfb8aa3b, v6
	v_exp_f32_e32 v9, v9
	v_mul_f32_e32 v4, v5, v13
	v_add_f32_e32 v8, 1.0, v9
	v_rcp_f32_e32 v11, v8
	v_mul_f32_e32 v1, v4, v1
	v_mul_f32_e32 v5, 0xbfb8aa3b, v7
	v_cvt_pk_bf16_f32 v0, v0, v1
	v_exp_f32_e32 v5, v5
	s_nop 0
	v_add_f32_e32 v5, 1.0, v5
	v_rcp_f32_e32 v10, v5
	v_mul_f32_e32 v1, v6, v11
	v_mul_f32_e32 v1, v1, v2
	v_mul_f32_e32 v2, v7, v10
	v_mul_f32_e32 v2, v2, v3
	v_cvt_pk_bf16_f32 v1, v1, v2
	global_store_dwordx2 v[16:17], v[0:1], off offset:32
	s_and_b64 vcc, exec, s[4:5]
	v_mov_b32_e32 v4, v180
	s_mov_b32 s82, s50
	v_mov_b32_e32 v198, v192
	v_mov_b64_e32 v[2:3], v[196:197]
	v_mov_b64_e32 v[0:1], v[194:195]
	s_cbranch_vccnz .LBB0_1752

.LBB0_1739:
	v_mbcnt_lo_u32_b32 v8, -1, 0
	v_mbcnt_hi_u32_b32 v8, -1, v8
	v_lshlrev_b32_e32 v8, 2, v8
	v_add_u32_e32 v8, 0x22000, v8
	ds_read_b32 v9, v8
	s_mov_b32 s52, 0x78
	s_mov_b32 s53, 0x22074
	s_mov_b32 s51, 31
	s_mov_b32 s50, 32
	s_mov_b32 s9, 32
	s_mov_b32 s50, 0x22080
	s_waitcnt lgkmcnt(0)
	v_cmp_ge_i32_e32 vcc, s8, v9
	s_and_b32 s52, vcc_lo, -2
	s_bcnt1_i32_b32 s52, s52
	v_mov_b32_e32 v180, s52
	s_mov_b32 s52, 0x78
.LBB0_1741:
	v_lshlrev_b32_e32 v5, 2, v180
	v_add_u32_e32 v5, 0, v5
	v_add_u32_e32 v5, 0x22000, v5
	ds_read2_b32 v[8:9], v5 offset1:40
	ds_read_b32 v6, v5 offset:320
	s_waitcnt lgkmcnt(0)
	v_readfirstlane_b32 s9, v9
	s_abs_i32 s50, s9
	v_cvt_f32_u32_e32 v7, s50
	s_sub_i32 s53, 0, s50
	v_readfirstlane_b32 s51, v8
	s_sub_i32 s51, s8, s51
	v_rcp_iflag_f32_e32 v7, v7
	s_abs_i32 s52, s51
	s_xor_b32 s8, s51, s9
	s_ashr_i32 s8, s8, 31
	v_mul_f32_e32 v7, 0x4f7ffffe, v7
	v_cvt_u32_f32_e32 v7, v7
	s_nop 0
	v_readfirstlane_b32 s83, v7
	s_mul_i32 s53, s53, s83
	s_mul_hi_u32 s53, s83, s53
	s_add_i32 s83, s83, s53
	s_mul_hi_u32 s53, s52, s83
	s_mul_i32 s83, s53, s50
	s_sub_i32 s52, s52, s83
	s_add_i32 s84, s53, 1
	s_sub_i32 s83, s52, s50
	s_cmp_ge_u32 s52, s50
	s_cselect_b32 s53, s84, s53
	s_cselect_b32 s52, s83, s52
	s_add_i32 s83, s53, 1
	s_cmp_ge_u32 s52, s50
	s_cselect_b32 s50, s83, s53
	s_xor_b32 s50, s50, s8
	s_sub_i32 s8, s50, s8
	s_mul_i32 s9, s8, s9
	s_sub_i32 s9, s51, s9
	s_and_b64 vcc, exec, s[20:21]
	s_lshl_b32 s50, s9, 8
	s_cbranch_vccz .LBB0_1751
	ds_read_b32 v5, v5 offset:480
	v_lshlrev_b64 v[8:9], 17, v[180:181]
	s_ashr_i32 s51, s50, 31
	v_lshl_add_u64 v[8:9], s[16:17], 0, v[8:9]
	s_lshl_b64 s[52:53], s[50:51], 2
	v_lshl_add_u64 v[190:191], v[8:9], 0, s[52:53]
	s_waitcnt lgkmcnt(0)
	v_subrev_u32_e32 v193, s50, v5
	v_add_u32_e32 v192, s50, v6
	v_mov_b64_e32 v[194:195], s[12:13]
	s_cbranch_execnz .LBB0_1745

.LBB0_1815:
	v_mbcnt_lo_u32_b32 v2, -1, 0
	v_mbcnt_hi_u32_b32 v2, -1, v2
	v_lshlrev_b32_e32 v2, 2, v2
	v_add_u32_e32 v2, 0x22000, v2
	ds_read_b32 v3, v2
	s_mov_b32 s16, 0x78
	s_mov_b32 s17, 0x22074
	s_mov_b32 s13, 31
	s_mov_b32 s12, 32
	s_mov_b32 s5, 0x22080
	s_waitcnt lgkmcnt(0)
	v_cmp_ge_i32_e32 vcc, s4, v3
	s_and_b32 s16, vcc_lo, -2
	s_bcnt1_i32_b32 s16, s16
	v_mov_b32_e32 v128, s16
	s_mov_b32 s16, 0x78
.LBB0_1817:
	v_ashrrev_i32_e32 v1, 31, v13
	v_lshrrev_b32_e32 v1, 26, v1
	v_add_u32_e32 v1, v13, v1
	v_ashrrev_i32_e32 v14, 6, v1
	v_bfe_i32 v1, v13, 27, 1
	v_lshlrev_b32_e32 v0, 4, v13
	v_lshrrev_b32_e32 v1, 22, v1
	v_add_u32_e32 v1, v0, v1
	v_and_b32_e32 v1, 0xfffffc00, v1
	v_sub_u32_e32 v1, v0, v1
	v_lshrrev_b32_e32 v2, 4, v1
	v_bitop3_b32 v1, v2, v1, 32 bitop3:0x6c
	v_ashrrev_i32_e32 v3, 31, v1
	v_lshrrev_b32_e32 v3, 26, v3
	v_add_u32_e32 v3, v1, v3
	v_ashrrev_i32_e32 v13, 6, v3
	v_and_b32_e32 v3, 0xc0, v3
	v_sub_u32_e32 v1, v1, v3
	v_mov_b32_e32 v3, 1
	v_lshlrev_b32_e32 v2, 3, v14
	v_lshlrev_b32_e32 v4, 5, v14
	v_ashrrev_i16_sdwa v1, v3, sext(v1) dst_sel:DWORD dst_unused:UNUSED_PAD src0_sel:DWORD src1_sel:BYTE_0
	v_and_b32_e32 v2, 0x1ffff0, v2
	v_and_b32_e32 v4, 32, v4
	v_bfe_i32 v15, v1, 0, 16
	v_add_u32_e32 v1, v4, v15
	v_add_lshl_u32 v2, v13, v2, 11
	v_add_u32_e32 v0, 0x2000, v0
	v_lshl_add_u32 v130, v1, 1, v2
	v_ashrrev_i32_e32 v1, 31, v0
	v_lshrrev_b32_e32 v1, 22, v1
	v_add_u32_e32 v1, v0, v1
	v_ashrrev_i32_e32 v16, 10, v1
	v_mul_i32_i24_e32 v1, 0x400, v16
	v_sub_u32_e32 v0, v0, v1
	v_lshrrev_b32_e32 v1, 4, v0
	v_bitop3_b32 v0, v1, v0, 32 bitop3:0x6c
	v_lshlrev_b32_e32 v1, 3, v16
	v_and_b32_e32 v2, 0x1ffff0, v1
	v_ashrrev_i32_e32 v1, 31, v0
	v_lshrrev_b32_e32 v1, 26, v1
	v_add_u32_e32 v1, v0, v1
	v_ashrrev_i32_e32 v17, 6, v1
	v_and_b32_e32 v1, 0xc0, v1
	v_sub_u32_e32 v0, v0, v1
	v_ashrrev_i16_sdwa v3, v3, sext(v0) dst_sel:DWORD dst_unused:UNUSED_PAD src0_sel:DWORD src1_sel:BYTE_0
	v_lshlrev_b32_e32 v0, 2, v128
	v_add_u32_e32 v0, 0, v0
	v_add_u32_e32 v5, 0x22000, v0
	ds_read2_b32 v[0:1], v5 offset1:40
	s_ashr_i32 s23, s46, 6
	s_ashr_i32 s22, s46, 8
	s_lshl_b32 s52, s23, 10
	v_mov_b32_e32 v129, 0
	s_waitcnt lgkmcnt(0)
	v_readfirstlane_b32 s5, v1
	s_abs_i32 s12, s5
	v_cvt_f32_u32_e32 v1, s12
	v_readfirstlane_b32 s13, v0
	s_sub_i32 s17, 0, s12
	s_sub_i32 s13, s4, s13
	v_rcp_iflag_f32_e32 v1, v1
	s_abs_i32 s16, s13
	s_xor_b32 s4, s13, s5
	s_ashr_i32 s4, s4, 31
	v_mul_f32_e32 v0, 0x4f7ffffe, v1
	v_cvt_u32_f32_e32 v0, v0
	v_lshlrev_b32_e32 v4, 5, v16
	v_and_b32_e32 v4, 32, v4
	v_bfe_i32 v18, v3, 0, 16
	v_readfirstlane_b32 s18, v0
	s_mul_i32 s17, s17, s18
	s_mul_hi_u32 s17, s18, s17
	s_add_i32 s18, s18, s17
	s_mul_hi_u32 s17, s16, s18
	s_mul_i32 s18, s17, s12
	s_sub_i32 s16, s16, s18
	s_add_i32 s18, s17, 1
	s_sub_i32 s19, s16, s12
	s_cmp_ge_u32 s16, s12
	s_cselect_b32 s17, s18, s17
	s_cselect_b32 s16, s19, s16
	s_add_i32 s18, s17, 1
	s_cmp_ge_u32 s16, s12
	s_cselect_b32 s12, s18, s17
	s_xor_b32 s12, s12, s4
	ds_read_b32 v0, v5 offset:320
	s_sub_i32 s4, s12, s4
	s_mul_i32 s5, s4, s5
	s_sub_i32 s5, s13, s5
	s_lshl_b32 s5, s5, 8
	s_waitcnt lgkmcnt(0)
	v_add_u32_e32 v140, s5, v0
	v_lshlrev_b64 v[0:1], 22, v[128:129]
	s_ashr_i32 s5, s4, 31
	v_lshl_add_u64 v[0:1], s[10:11], 0, v[0:1]
	s_lshl_b64 s[12:13], s[4:5], 19
	v_add_u32_e32 v3, v4, v18
	v_add_lshl_u32 v2, v17, v2, 11
	v_lshl_add_u64 v[0:1], v[0:1], 0, s[12:13]
	v_ashrrev_i32_e32 v141, 31, v140
	s_add_i32 s53, s52, 0
	v_lshl_add_u32 v132, v3, 1, v2
	v_lshlrev_b64 v[2:3], 11, v[140:141]
	s_add_i32 m0, s53, 0x10000
	v_readfirstlane_b32 s12, v0
	v_readfirstlane_b32 s13, v1
	v_lshl_add_u64 v[2:3], s[8:9], 0, v[2:3]
	s_add_i32 s54, s53, 0x2000
	s_add_i32 s55, s53, 0x4000
	s_add_i32 s56, s53, 0x6000
	v_mov_b32_e32 v131, v129
	global_load_lds_dwordx4 v130, s[12:13]
	s_add_i32 m0, s53, 0x12000
	v_mov_b32_e32 v133, v129
	global_load_lds_dwordx4 v132, s[12:13]
	v_readfirstlane_b32 s12, v2
	v_readfirstlane_b32 s13, v3
	s_mov_b32 m0, s53
	s_mov_b32 s57, 0
	s_mov_b32 s58, 0x10000
	v_lshl_add_u64 v[10:11], v[0:1], 0, v[130:131]
	v_lshl_add_u64 v[8:9], v[0:1], 0, v[132:133]
	global_load_lds_dwordx4 v130, s[12:13]
	s_mov_b32 m0, s54
	v_lshl_add_u64 v[6:7], v[2:3], 0, v[130:131]
	global_load_lds_dwordx4 v132, s[12:13]
	s_mov_b64 s[12:13], 0x40000
	v_lshl_add_u64 v[4:5], v[0:1], 0, s[12:13]
	s_add_i32 m0, s53, 0x14000
	v_readfirstlane_b32 s16, v4
	v_readfirstlane_b32 s17, v5
	v_lshl_add_u64 v[4:5], v[2:3], 0, s[12:13]
	s_nop 3
	global_load_lds_dwordx4 v130, s[16:17]
	s_add_i32 m0, s53, 0x16000
	s_cmp_eq_u32 s22, 1
	global_load_lds_dwordx4 v132, s[16:17]
	v_readfirstlane_b32 s16, v4
	v_readfirstlane_b32 s17, v5
	s_mov_b32 m0, s55
	v_lshl_add_u64 v[4:5], v[2:3], 0, v[132:133]
	s_nop 2
	global_load_lds_dwordx4 v130, s[16:17]
	s_mov_b32 m0, s56
	s_nop 0
	global_load_lds_dwordx4 v132, s[16:17]
	s_cbranch_scc0 .LBB0_1820
	s_barrier

.LBB0_1827:
	v_mbcnt_lo_u32_b32 v6, -1, 0
	v_mbcnt_hi_u32_b32 v6, -1, v6
	v_lshlrev_b32_e32 v6, 2, v6
	v_add_u32_e32 v6, 0x22000, v6
	ds_read_b32 v7, v6
	s_mov_b32 s76, 0x78
	s_mov_b32 s77, 0x22074
	s_mov_b32 s75, 31
	s_mov_b32 s73, 32
	s_mov_b32 s45, 32
	s_mov_b32 s73, 0x22080
	s_waitcnt lgkmcnt(0)
	v_cmp_ge_i32_e32 vcc, s44, v7
	s_and_b32 s76, vcc_lo, -2
	s_bcnt1_i32_b32 s76, s76
	v_mov_b32_e32 v128, s76
	s_mov_b32 s76, 0x78
.LBB0_1829:
	v_lshlrev_b32_e32 v4, 2, v128
	v_add_u32_e32 v4, 0, v4
	v_add_u32_e32 v8, 0x22000, v4
	ds_read2_b32 v[4:5], v8 offset1:40
	ds_read_b32 v8, v8 offset:320
	v_lshlrev_b64 v[6:7], 22, v[128:129]
	v_lshl_add_u64 v[6:7], s[10:11], 0, v[6:7]
	s_waitcnt lgkmcnt(0)
	v_readfirstlane_b32 s45, v5
	s_abs_i32 s73, s45
	v_cvt_f32_u32_e32 v5, s73
	v_readfirstlane_b32 s75, v4
	s_sub_i32 s77, 0, s73
	s_sub_i32 s75, s44, s75
	v_rcp_iflag_f32_e32 v5, v5
	s_abs_i32 s76, s75
	s_xor_b32 s44, s75, s45
	s_ashr_i32 s44, s44, 31
	v_mul_f32_e32 v4, 0x4f7ffffe, v5
	v_cvt_u32_f32_e32 v4, v4
	s_nop 0
	v_readfirstlane_b32 s78, v4
	s_mul_i32 s77, s77, s78
	s_mul_hi_u32 s77, s78, s77
	s_add_i32 s78, s78, s77
	s_mul_hi_u32 s77, s76, s78
	s_mul_i32 s78, s77, s73
	s_sub_i32 s76, s76, s78
	s_add_i32 s79, s77, 1
	s_sub_i32 s78, s76, s73
	s_cmp_ge_u32 s76, s73
	s_cselect_b32 s77, s79, s77
	s_cselect_b32 s76, s78, s76
	s_add_i32 s78, s77, 1
	s_cmp_ge_u32 s76, s73
	s_cselect_b32 s73, s78, s77
	s_xor_b32 s73, s73, s44
	s_sub_i32 s44, s73, s44
	s_mul_i32 s76, s44, s45
	s_sub_i32 s75, s75, s76
	s_lshl_b32 s75, s75, 8
	v_add_u32_e32 v142, s75, v8
	s_ashr_i32 s45, s44, 31
	v_ashrrev_i32_e32 v143, 31, v142
	s_lshl_b32 s73, s44, 8
	s_lshl_b64 s[44:45], s[44:45], 19
	v_lshlrev_b64 v[4:5], 11, v[142:143]
	v_lshl_add_u64 v[144:145], v[6:7], 0, s[44:45]
	v_lshl_add_u64 v[146:147], s[8:9], 0, v[4:5]
